# P6' panel rendezvous: one arrival + one poller per workgroup (panel count 8); rest as v056
# speedup vs baseline: 1.0014x; 1.0014x over previous
.LBB0_677:
	s_lshl_b32 s3, s2, 8
	s_add_i32 s3, s3, s77
	v_add_u32_e32 v181, s3, v172
	v_lshl_add_u32 v185, v173, 3, s44
	v_lshlrev_b32_e32 v253, 2, v181
	v_lshlrev_b32_e32 v252, 2, v185
	v_lshlrev_b32_e32 v187, 12, v181
	v_lshl_add_u32 v187, v185, 1, v187
	v_lshlrev_b32_e32 v181, 13, v181
	s_lshl_b32 s3, s44, 2
	v_lshl_add_u32 v185, v173, 4, s3
	v_add_u32_e32 v185, v185, v181
	global_load_dword v164, v253, s[12:13]
	global_load_dword v165, v253, s[12:13] offset:64
	global_load_dword v166, v253, s[12:13] offset:128
	global_load_dword v167, v253, s[12:13] offset:192
	global_load_dword v168, v253, s[12:13] offset:512
	global_load_dword v169, v253, s[12:13] offset:576
	global_load_dword v170, v253, s[12:13] offset:640
	global_load_dword v171, v253, s[12:13] offset:704
	global_load_dwordx4 v[148:151], v252, s[14:15] offset:0
	global_load_dwordx4 v[152:155], v252, s[14:15] offset:16
	global_load_dwordx4 v[156:159], v252, s[14:15] offset:512
	global_load_dwordx4 v[160:163], v252, s[14:15] offset:528
	s_mov_b32 s98, s18
	s_mov_b32 s99, s19
	s_nop 0
	global_load_dwordx4 v[188:191], v187, s[98:99]
	global_load_dwordx4 v[192:195], v187, s[98:99] offset:256
	s_add_u32 s98, s18, 0x10000
	s_addc_u32 s99, s19, 0
	s_nop 0
	global_load_dwordx4 v[196:199], v187, s[98:99]
	global_load_dwordx4 v[200:203], v187, s[98:99] offset:256
	s_add_u32 s98, s18, 0x20000
	s_addc_u32 s99, s19, 0
	s_nop 0
	global_load_dwordx4 v[204:207], v187, s[98:99]
	global_load_dwordx4 v[208:211], v187, s[98:99] offset:256
	s_add_u32 s98, s18, 0x30000
	s_addc_u32 s99, s19, 0
	s_nop 0
	global_load_dwordx4 v[212:215], v187, s[98:99]
	global_load_dwordx4 v[216:219], v187, s[98:99] offset:256
	s_add_u32 s98, s18, 0x80000
	s_addc_u32 s99, s19, 0
	s_nop 0
	global_load_dwordx4 v[220:223], v187, s[98:99]
	global_load_dwordx4 v[224:227], v187, s[98:99] offset:256
	s_add_u32 s98, s18, 0x90000
	s_addc_u32 s99, s19, 0
	s_nop 0
	global_load_dwordx4 v[228:231], v187, s[98:99]
	global_load_dwordx4 v[232:235], v187, s[98:99] offset:256
	s_add_u32 s98, s18, 0xa0000
	s_addc_u32 s99, s19, 0
	s_nop 0
	global_load_dwordx4 v[236:239], v187, s[98:99]
	global_load_dwordx4 v[240:243], v187, s[98:99] offset:256
	s_add_u32 s98, s18, 0xb0000
	s_addc_u32 s99, s19, 0
	s_nop 0
	global_load_dwordx4 v[244:247], v187, s[98:99]
	global_load_dwordx4 v[248:251], v187, s[98:99] offset:256
	s_waitcnt vmcnt(15)
	v_fmamk_f32 v184, v164, 0x3a000000, v177
	v_rcp_f32_e32 v184, v184
	v_and_b32_e32 v129, 0xffff0000, v188
	v_lshlrev_b32_e32 v128, 16, v188
	v_and_b32_e32 v131, 0xffff0000, v189
	v_lshlrev_b32_e32 v130, 16, v189
	v_and_b32_e32 v133, 0xffff0000, v190
	v_lshlrev_b32_e32 v132, 16, v190
	v_and_b32_e32 v135, 0xffff0000, v191
	v_lshlrev_b32_e32 v134, 16, v191
	v_pk_mul_f32 v[128:129], v[148:149], v[128:129]
	v_pk_mul_f32 v[130:131], v[150:151], v[130:131]
	v_pk_mul_f32 v[132:133], v[152:153], v[132:133]
	v_pk_mul_f32 v[134:135], v[154:155], v[134:135]
	v_pk_fma_f32 v[124:125], v[124:125], v[184:185], v[128:129] op_sel_hi:[1,0,1]
	v_pk_fma_f32 v[126:127], v[126:127], v[184:185], v[130:131] op_sel_hi:[1,0,1]
	v_pk_fma_f32 v[120:121], v[120:121], v[184:185], v[132:133] op_sel_hi:[1,0,1]
	v_pk_fma_f32 v[122:123], v[122:123], v[184:185], v[134:135] op_sel_hi:[1,0,1]
	v_pk_mul_f32 v[182:183], v[124:125], v[124:125]
	v_pk_fma_f32 v[182:183], v[126:127], v[126:127], v[182:183]
	v_pk_fma_f32 v[182:183], v[120:121], v[120:121], v[182:183]
	v_pk_fma_f32 v[182:183], v[122:123], v[122:123], v[182:183]
	s_waitcnt vmcnt(14)
	v_and_b32_e32 v129, 0xffff0000, v192
	v_lshlrev_b32_e32 v128, 16, v192
	v_and_b32_e32 v131, 0xffff0000, v193
	v_lshlrev_b32_e32 v130, 16, v193
	v_and_b32_e32 v133, 0xffff0000, v194
	v_lshlrev_b32_e32 v132, 16, v194
	v_and_b32_e32 v135, 0xffff0000, v195
	v_lshlrev_b32_e32 v134, 16, v195
	v_pk_mul_f32 v[128:129], v[156:157], v[128:129]
	v_pk_mul_f32 v[130:131], v[158:159], v[130:131]
	v_pk_mul_f32 v[132:133], v[160:161], v[132:133]
	v_pk_mul_f32 v[134:135], v[162:163], v[134:135]
	v_pk_fma_f32 v[116:117], v[116:117], v[184:185], v[128:129] op_sel_hi:[1,0,1]
	v_pk_fma_f32 v[118:119], v[118:119], v[184:185], v[130:131] op_sel_hi:[1,0,1]
	v_pk_fma_f32 v[112:113], v[112:113], v[184:185], v[132:133] op_sel_hi:[1,0,1]
	v_pk_fma_f32 v[114:115], v[114:115], v[184:185], v[134:135] op_sel_hi:[1,0,1]
	v_pk_fma_f32 v[182:183], v[116:117], v[116:117], v[182:183]
	v_pk_fma_f32 v[182:183], v[118:119], v[118:119], v[182:183]
	v_pk_fma_f32 v[182:183], v[112:113], v[112:113], v[182:183]
	v_pk_fma_f32 v[182:183], v[114:115], v[114:115], v[182:183]
	v_add_f32_e32 v164, v182, v183
	s_waitcnt vmcnt(13)
	v_fmamk_f32 v184, v165, 0x3a000000, v177
	v_rcp_f32_e32 v184, v184
	v_and_b32_e32 v129, 0xffff0000, v196
	v_lshlrev_b32_e32 v128, 16, v196
	v_and_b32_e32 v131, 0xffff0000, v197
	v_lshlrev_b32_e32 v130, 16, v197
	v_and_b32_e32 v133, 0xffff0000, v198
	v_lshlrev_b32_e32 v132, 16, v198
	v_and_b32_e32 v135, 0xffff0000, v199
	v_lshlrev_b32_e32 v134, 16, v199
	v_pk_mul_f32 v[128:129], v[148:149], v[128:129]
	v_pk_mul_f32 v[130:131], v[150:151], v[130:131]
	v_pk_mul_f32 v[132:133], v[152:153], v[132:133]
	v_pk_mul_f32 v[134:135], v[154:155], v[134:135]
	v_pk_fma_f32 v[108:109], v[108:109], v[184:185], v[128:129] op_sel_hi:[1,0,1]
	v_pk_fma_f32 v[110:111], v[110:111], v[184:185], v[130:131] op_sel_hi:[1,0,1]
	v_pk_fma_f32 v[104:105], v[104:105], v[184:185], v[132:133] op_sel_hi:[1,0,1]
	v_pk_fma_f32 v[106:107], v[106:107], v[184:185], v[134:135] op_sel_hi:[1,0,1]
	v_pk_mul_f32 v[182:183], v[108:109], v[108:109]
	v_pk_fma_f32 v[182:183], v[110:111], v[110:111], v[182:183]
	v_pk_fma_f32 v[182:183], v[104:105], v[104:105], v[182:183]
	v_pk_fma_f32 v[182:183], v[106:107], v[106:107], v[182:183]
	s_waitcnt vmcnt(12)
	v_and_b32_e32 v129, 0xffff0000, v200
	v_lshlrev_b32_e32 v128, 16, v200
	v_and_b32_e32 v131, 0xffff0000, v201
	v_lshlrev_b32_e32 v130, 16, v201
	v_and_b32_e32 v133, 0xffff0000, v202
	v_lshlrev_b32_e32 v132, 16, v202
	v_and_b32_e32 v135, 0xffff0000, v203
	v_lshlrev_b32_e32 v134, 16, v203
	v_pk_mul_f32 v[128:129], v[156:157], v[128:129]
	v_pk_mul_f32 v[130:131], v[158:159], v[130:131]
	v_pk_mul_f32 v[132:133], v[160:161], v[132:133]
	v_pk_mul_f32 v[134:135], v[162:163], v[134:135]
	v_pk_fma_f32 v[100:101], v[100:101], v[184:185], v[128:129] op_sel_hi:[1,0,1]
	v_pk_fma_f32 v[102:103], v[102:103], v[184:185], v[130:131] op_sel_hi:[1,0,1]
	v_pk_fma_f32 v[96:97], v[96:97], v[184:185], v[132:133] op_sel_hi:[1,0,1]
	v_pk_fma_f32 v[98:99], v[98:99], v[184:185], v[134:135] op_sel_hi:[1,0,1]
	v_pk_fma_f32 v[182:183], v[100:101], v[100:101], v[182:183]
	v_pk_fma_f32 v[182:183], v[102:103], v[102:103], v[182:183]
	v_pk_fma_f32 v[182:183], v[96:97], v[96:97], v[182:183]
	v_pk_fma_f32 v[182:183], v[98:99], v[98:99], v[182:183]
	v_add_f32_e32 v165, v182, v183
	s_waitcnt vmcnt(11)
	v_fmamk_f32 v184, v166, 0x3a000000, v177
	v_rcp_f32_e32 v184, v184
	v_and_b32_e32 v129, 0xffff0000, v204
	v_lshlrev_b32_e32 v128, 16, v204
	v_and_b32_e32 v131, 0xffff0000, v205
	v_lshlrev_b32_e32 v130, 16, v205
	v_and_b32_e32 v133, 0xffff0000, v206
	v_lshlrev_b32_e32 v132, 16, v206
	v_and_b32_e32 v135, 0xffff0000, v207
	v_lshlrev_b32_e32 v134, 16, v207
	v_pk_mul_f32 v[128:129], v[148:149], v[128:129]
	v_pk_mul_f32 v[130:131], v[150:151], v[130:131]
	v_pk_mul_f32 v[132:133], v[152:153], v[132:133]
	v_pk_mul_f32 v[134:135], v[154:155], v[134:135]
	v_pk_fma_f32 v[92:93], v[92:93], v[184:185], v[128:129] op_sel_hi:[1,0,1]
	v_pk_fma_f32 v[94:95], v[94:95], v[184:185], v[130:131] op_sel_hi:[1,0,1]
	v_pk_fma_f32 v[88:89], v[88:89], v[184:185], v[132:133] op_sel_hi:[1,0,1]
	v_pk_fma_f32 v[90:91], v[90:91], v[184:185], v[134:135] op_sel_hi:[1,0,1]
	v_pk_mul_f32 v[182:183], v[92:93], v[92:93]
	v_pk_fma_f32 v[182:183], v[94:95], v[94:95], v[182:183]
	v_pk_fma_f32 v[182:183], v[88:89], v[88:89], v[182:183]
	v_pk_fma_f32 v[182:183], v[90:91], v[90:91], v[182:183]
	s_waitcnt vmcnt(10)
	v_and_b32_e32 v129, 0xffff0000, v208
	v_lshlrev_b32_e32 v128, 16, v208
	v_and_b32_e32 v131, 0xffff0000, v209
	v_lshlrev_b32_e32 v130, 16, v209
	v_and_b32_e32 v133, 0xffff0000, v210
	v_lshlrev_b32_e32 v132, 16, v210
	v_and_b32_e32 v135, 0xffff0000, v211
	v_lshlrev_b32_e32 v134, 16, v211
	v_pk_mul_f32 v[128:129], v[156:157], v[128:129]
	v_pk_mul_f32 v[130:131], v[158:159], v[130:131]
	v_pk_mul_f32 v[132:133], v[160:161], v[132:133]
	v_pk_mul_f32 v[134:135], v[162:163], v[134:135]
	v_pk_fma_f32 v[84:85], v[84:85], v[184:185], v[128:129] op_sel_hi:[1,0,1]
	v_pk_fma_f32 v[86:87], v[86:87], v[184:185], v[130:131] op_sel_hi:[1,0,1]
	v_pk_fma_f32 v[80:81], v[80:81], v[184:185], v[132:133] op_sel_hi:[1,0,1]
	v_pk_fma_f32 v[82:83], v[82:83], v[184:185], v[134:135] op_sel_hi:[1,0,1]
	v_pk_fma_f32 v[182:183], v[84:85], v[84:85], v[182:183]
	v_pk_fma_f32 v[182:183], v[86:87], v[86:87], v[182:183]
	v_pk_fma_f32 v[182:183], v[80:81], v[80:81], v[182:183]
	v_pk_fma_f32 v[182:183], v[82:83], v[82:83], v[182:183]
	v_add_f32_e32 v166, v182, v183
	s_waitcnt vmcnt(9)
	v_fmamk_f32 v184, v167, 0x3a000000, v177
	v_rcp_f32_e32 v184, v184
	v_and_b32_e32 v129, 0xffff0000, v212
	v_lshlrev_b32_e32 v128, 16, v212
	v_and_b32_e32 v131, 0xffff0000, v213
	v_lshlrev_b32_e32 v130, 16, v213
	v_and_b32_e32 v133, 0xffff0000, v214
	v_lshlrev_b32_e32 v132, 16, v214
	v_and_b32_e32 v135, 0xffff0000, v215
	v_lshlrev_b32_e32 v134, 16, v215
	v_pk_mul_f32 v[128:129], v[148:149], v[128:129]
	v_pk_mul_f32 v[130:131], v[150:151], v[130:131]
	v_pk_mul_f32 v[132:133], v[152:153], v[132:133]
	v_pk_mul_f32 v[134:135], v[154:155], v[134:135]
	v_pk_fma_f32 v[76:77], v[76:77], v[184:185], v[128:129] op_sel_hi:[1,0,1]
	v_pk_fma_f32 v[78:79], v[78:79], v[184:185], v[130:131] op_sel_hi:[1,0,1]
	v_pk_fma_f32 v[72:73], v[72:73], v[184:185], v[132:133] op_sel_hi:[1,0,1]
	v_pk_fma_f32 v[74:75], v[74:75], v[184:185], v[134:135] op_sel_hi:[1,0,1]
	v_pk_mul_f32 v[182:183], v[76:77], v[76:77]
	v_pk_fma_f32 v[182:183], v[78:79], v[78:79], v[182:183]
	v_pk_fma_f32 v[182:183], v[72:73], v[72:73], v[182:183]
	v_pk_fma_f32 v[182:183], v[74:75], v[74:75], v[182:183]
	s_waitcnt vmcnt(8)
	v_and_b32_e32 v129, 0xffff0000, v216
	v_lshlrev_b32_e32 v128, 16, v216
	v_and_b32_e32 v131, 0xffff0000, v217
	v_lshlrev_b32_e32 v130, 16, v217
	v_and_b32_e32 v133, 0xffff0000, v218
	v_lshlrev_b32_e32 v132, 16, v218
	v_and_b32_e32 v135, 0xffff0000, v219
	v_lshlrev_b32_e32 v134, 16, v219
	v_pk_mul_f32 v[128:129], v[156:157], v[128:129]
	v_pk_mul_f32 v[130:131], v[158:159], v[130:131]
	v_pk_mul_f32 v[132:133], v[160:161], v[132:133]
	v_pk_mul_f32 v[134:135], v[162:163], v[134:135]
	v_pk_fma_f32 v[68:69], v[68:69], v[184:185], v[128:129] op_sel_hi:[1,0,1]
	v_pk_fma_f32 v[70:71], v[70:71], v[184:185], v[130:131] op_sel_hi:[1,0,1]
	v_pk_fma_f32 v[64:65], v[64:65], v[184:185], v[132:133] op_sel_hi:[1,0,1]
	v_pk_fma_f32 v[66:67], v[66:67], v[184:185], v[134:135] op_sel_hi:[1,0,1]
	v_pk_fma_f32 v[182:183], v[68:69], v[68:69], v[182:183]
	v_pk_fma_f32 v[182:183], v[70:71], v[70:71], v[182:183]
	v_pk_fma_f32 v[182:183], v[64:65], v[64:65], v[182:183]
	v_pk_fma_f32 v[182:183], v[66:67], v[66:67], v[182:183]
	v_add_f32_e32 v167, v182, v183
	s_waitcnt vmcnt(7)
	v_fmamk_f32 v184, v168, 0x3a000000, v177
	v_rcp_f32_e32 v184, v184
	v_and_b32_e32 v129, 0xffff0000, v220
	v_lshlrev_b32_e32 v128, 16, v220
	v_and_b32_e32 v131, 0xffff0000, v221
	v_lshlrev_b32_e32 v130, 16, v221
	v_and_b32_e32 v133, 0xffff0000, v222
	v_lshlrev_b32_e32 v132, 16, v222
	v_and_b32_e32 v135, 0xffff0000, v223
	v_lshlrev_b32_e32 v134, 16, v223
	v_pk_mul_f32 v[128:129], v[148:149], v[128:129]
	v_pk_mul_f32 v[130:131], v[150:151], v[130:131]
	v_pk_mul_f32 v[132:133], v[152:153], v[132:133]
	v_pk_mul_f32 v[134:135], v[154:155], v[134:135]
	v_pk_fma_f32 v[60:61], v[60:61], v[184:185], v[128:129] op_sel_hi:[1,0,1]
	v_pk_fma_f32 v[62:63], v[62:63], v[184:185], v[130:131] op_sel_hi:[1,0,1]
	v_pk_fma_f32 v[56:57], v[56:57], v[184:185], v[132:133] op_sel_hi:[1,0,1]
	v_pk_fma_f32 v[58:59], v[58:59], v[184:185], v[134:135] op_sel_hi:[1,0,1]
	v_pk_mul_f32 v[182:183], v[60:61], v[60:61]
	v_pk_fma_f32 v[182:183], v[62:63], v[62:63], v[182:183]
	v_pk_fma_f32 v[182:183], v[56:57], v[56:57], v[182:183]
	v_pk_fma_f32 v[182:183], v[58:59], v[58:59], v[182:183]
	s_waitcnt vmcnt(6)
	v_and_b32_e32 v129, 0xffff0000, v224
	v_lshlrev_b32_e32 v128, 16, v224
	v_and_b32_e32 v131, 0xffff0000, v225
	v_lshlrev_b32_e32 v130, 16, v225
	v_and_b32_e32 v133, 0xffff0000, v226
	v_lshlrev_b32_e32 v132, 16, v226
	v_and_b32_e32 v135, 0xffff0000, v227
	v_lshlrev_b32_e32 v134, 16, v227
	v_pk_mul_f32 v[128:129], v[156:157], v[128:129]
	v_pk_mul_f32 v[130:131], v[158:159], v[130:131]
	v_pk_mul_f32 v[132:133], v[160:161], v[132:133]
	v_pk_mul_f32 v[134:135], v[162:163], v[134:135]
	v_pk_fma_f32 v[52:53], v[52:53], v[184:185], v[128:129] op_sel_hi:[1,0,1]
	v_pk_fma_f32 v[54:55], v[54:55], v[184:185], v[130:131] op_sel_hi:[1,0,1]
	v_pk_fma_f32 v[48:49], v[48:49], v[184:185], v[132:133] op_sel_hi:[1,0,1]
	v_pk_fma_f32 v[50:51], v[50:51], v[184:185], v[134:135] op_sel_hi:[1,0,1]
	v_pk_fma_f32 v[182:183], v[52:53], v[52:53], v[182:183]
	v_pk_fma_f32 v[182:183], v[54:55], v[54:55], v[182:183]
	v_pk_fma_f32 v[182:183], v[48:49], v[48:49], v[182:183]
	v_pk_fma_f32 v[182:183], v[50:51], v[50:51], v[182:183]
	v_add_f32_e32 v168, v182, v183
	s_waitcnt vmcnt(5)
	v_fmamk_f32 v184, v169, 0x3a000000, v177
	v_rcp_f32_e32 v184, v184
	v_and_b32_e32 v129, 0xffff0000, v228
	v_lshlrev_b32_e32 v128, 16, v228
	v_and_b32_e32 v131, 0xffff0000, v229
	v_lshlrev_b32_e32 v130, 16, v229
	v_and_b32_e32 v133, 0xffff0000, v230
	v_lshlrev_b32_e32 v132, 16, v230
	v_and_b32_e32 v135, 0xffff0000, v231
	v_lshlrev_b32_e32 v134, 16, v231
	v_pk_mul_f32 v[128:129], v[148:149], v[128:129]
	v_pk_mul_f32 v[130:131], v[150:151], v[130:131]
	v_pk_mul_f32 v[132:133], v[152:153], v[132:133]
	v_pk_mul_f32 v[134:135], v[154:155], v[134:135]
	v_pk_fma_f32 v[44:45], v[44:45], v[184:185], v[128:129] op_sel_hi:[1,0,1]
	v_pk_fma_f32 v[46:47], v[46:47], v[184:185], v[130:131] op_sel_hi:[1,0,1]
	v_pk_fma_f32 v[40:41], v[40:41], v[184:185], v[132:133] op_sel_hi:[1,0,1]
	v_pk_fma_f32 v[42:43], v[42:43], v[184:185], v[134:135] op_sel_hi:[1,0,1]
	v_pk_mul_f32 v[182:183], v[44:45], v[44:45]
	v_pk_fma_f32 v[182:183], v[46:47], v[46:47], v[182:183]
	v_pk_fma_f32 v[182:183], v[40:41], v[40:41], v[182:183]
	v_pk_fma_f32 v[182:183], v[42:43], v[42:43], v[182:183]
	s_waitcnt vmcnt(4)
	v_and_b32_e32 v129, 0xffff0000, v232
	v_lshlrev_b32_e32 v128, 16, v232
	v_and_b32_e32 v131, 0xffff0000, v233
	v_lshlrev_b32_e32 v130, 16, v233
	v_and_b32_e32 v133, 0xffff0000, v234
	v_lshlrev_b32_e32 v132, 16, v234
	v_and_b32_e32 v135, 0xffff0000, v235
	v_lshlrev_b32_e32 v134, 16, v235
	v_pk_mul_f32 v[128:129], v[156:157], v[128:129]
	v_pk_mul_f32 v[130:131], v[158:159], v[130:131]
	v_pk_mul_f32 v[132:133], v[160:161], v[132:133]
	v_pk_mul_f32 v[134:135], v[162:163], v[134:135]
	v_pk_fma_f32 v[36:37], v[36:37], v[184:185], v[128:129] op_sel_hi:[1,0,1]
	v_pk_fma_f32 v[38:39], v[38:39], v[184:185], v[130:131] op_sel_hi:[1,0,1]
	v_pk_fma_f32 v[32:33], v[32:33], v[184:185], v[132:133] op_sel_hi:[1,0,1]
	v_pk_fma_f32 v[34:35], v[34:35], v[184:185], v[134:135] op_sel_hi:[1,0,1]
	v_pk_fma_f32 v[182:183], v[36:37], v[36:37], v[182:183]
	v_pk_fma_f32 v[182:183], v[38:39], v[38:39], v[182:183]
	v_pk_fma_f32 v[182:183], v[32:33], v[32:33], v[182:183]
	v_pk_fma_f32 v[182:183], v[34:35], v[34:35], v[182:183]
	v_add_f32_e32 v169, v182, v183
	s_waitcnt vmcnt(3)
	v_fmamk_f32 v184, v170, 0x3a000000, v177
	v_rcp_f32_e32 v184, v184
	v_and_b32_e32 v129, 0xffff0000, v236
	v_lshlrev_b32_e32 v128, 16, v236
	v_and_b32_e32 v131, 0xffff0000, v237
	v_lshlrev_b32_e32 v130, 16, v237
	v_and_b32_e32 v133, 0xffff0000, v238
	v_lshlrev_b32_e32 v132, 16, v238
	v_and_b32_e32 v135, 0xffff0000, v239
	v_lshlrev_b32_e32 v134, 16, v239
	v_pk_mul_f32 v[128:129], v[148:149], v[128:129]
	v_pk_mul_f32 v[130:131], v[150:151], v[130:131]
	v_pk_mul_f32 v[132:133], v[152:153], v[132:133]
	v_pk_mul_f32 v[134:135], v[154:155], v[134:135]
	v_pk_fma_f32 v[28:29], v[28:29], v[184:185], v[128:129] op_sel_hi:[1,0,1]
	v_pk_fma_f32 v[30:31], v[30:31], v[184:185], v[130:131] op_sel_hi:[1,0,1]
	v_pk_fma_f32 v[24:25], v[24:25], v[184:185], v[132:133] op_sel_hi:[1,0,1]
	v_pk_fma_f32 v[26:27], v[26:27], v[184:185], v[134:135] op_sel_hi:[1,0,1]
	v_pk_mul_f32 v[182:183], v[28:29], v[28:29]
	v_pk_fma_f32 v[182:183], v[30:31], v[30:31], v[182:183]
	v_pk_fma_f32 v[182:183], v[24:25], v[24:25], v[182:183]
	v_pk_fma_f32 v[182:183], v[26:27], v[26:27], v[182:183]
	s_waitcnt vmcnt(2)
	v_and_b32_e32 v129, 0xffff0000, v240
	v_lshlrev_b32_e32 v128, 16, v240
	v_and_b32_e32 v131, 0xffff0000, v241
	v_lshlrev_b32_e32 v130, 16, v241
	v_and_b32_e32 v133, 0xffff0000, v242
	v_lshlrev_b32_e32 v132, 16, v242
	v_and_b32_e32 v135, 0xffff0000, v243
	v_lshlrev_b32_e32 v134, 16, v243
	v_pk_mul_f32 v[128:129], v[156:157], v[128:129]
	v_pk_mul_f32 v[130:131], v[158:159], v[130:131]
	v_pk_mul_f32 v[132:133], v[160:161], v[132:133]
	v_pk_mul_f32 v[134:135], v[162:163], v[134:135]
	v_pk_fma_f32 v[20:21], v[20:21], v[184:185], v[128:129] op_sel_hi:[1,0,1]
	v_pk_fma_f32 v[22:23], v[22:23], v[184:185], v[130:131] op_sel_hi:[1,0,1]
	v_pk_fma_f32 v[16:17], v[16:17], v[184:185], v[132:133] op_sel_hi:[1,0,1]
	v_pk_fma_f32 v[18:19], v[18:19], v[184:185], v[134:135] op_sel_hi:[1,0,1]
	v_pk_fma_f32 v[182:183], v[20:21], v[20:21], v[182:183]
	v_pk_fma_f32 v[182:183], v[22:23], v[22:23], v[182:183]
	v_pk_fma_f32 v[182:183], v[16:17], v[16:17], v[182:183]
	v_pk_fma_f32 v[182:183], v[18:19], v[18:19], v[182:183]
	v_add_f32_e32 v170, v182, v183
	s_waitcnt vmcnt(1)
	v_fmamk_f32 v184, v171, 0x3a000000, v177
	v_rcp_f32_e32 v184, v184
	v_and_b32_e32 v129, 0xffff0000, v244
	v_lshlrev_b32_e32 v128, 16, v244
	v_and_b32_e32 v131, 0xffff0000, v245
	v_lshlrev_b32_e32 v130, 16, v245
	v_and_b32_e32 v133, 0xffff0000, v246
	v_lshlrev_b32_e32 v132, 16, v246
	v_and_b32_e32 v135, 0xffff0000, v247
	v_lshlrev_b32_e32 v134, 16, v247
	v_pk_mul_f32 v[128:129], v[148:149], v[128:129]
	v_pk_mul_f32 v[130:131], v[150:151], v[130:131]
	v_pk_mul_f32 v[132:133], v[152:153], v[132:133]
	v_pk_mul_f32 v[134:135], v[154:155], v[134:135]
	v_pk_fma_f32 v[12:13], v[12:13], v[184:185], v[128:129] op_sel_hi:[1,0,1]
	v_pk_fma_f32 v[14:15], v[14:15], v[184:185], v[130:131] op_sel_hi:[1,0,1]
	v_pk_fma_f32 v[8:9], v[8:9], v[184:185], v[132:133] op_sel_hi:[1,0,1]
	v_pk_fma_f32 v[10:11], v[10:11], v[184:185], v[134:135] op_sel_hi:[1,0,1]
	v_pk_mul_f32 v[182:183], v[12:13], v[12:13]
	v_pk_fma_f32 v[182:183], v[14:15], v[14:15], v[182:183]
	v_pk_fma_f32 v[182:183], v[8:9], v[8:9], v[182:183]
	v_pk_fma_f32 v[182:183], v[10:11], v[10:11], v[182:183]
	s_waitcnt vmcnt(0)
	v_and_b32_e32 v129, 0xffff0000, v248
	v_lshlrev_b32_e32 v128, 16, v248
	v_and_b32_e32 v131, 0xffff0000, v249
	v_lshlrev_b32_e32 v130, 16, v249
	v_and_b32_e32 v133, 0xffff0000, v250
	v_lshlrev_b32_e32 v132, 16, v250
	v_and_b32_e32 v135, 0xffff0000, v251
	v_lshlrev_b32_e32 v134, 16, v251
	v_pk_mul_f32 v[128:129], v[156:157], v[128:129]
	v_pk_mul_f32 v[130:131], v[158:159], v[130:131]
	v_pk_mul_f32 v[132:133], v[160:161], v[132:133]
	v_pk_mul_f32 v[134:135], v[162:163], v[134:135]
	v_pk_fma_f32 v[4:5], v[4:5], v[184:185], v[128:129] op_sel_hi:[1,0,1]
	v_pk_fma_f32 v[6:7], v[6:7], v[184:185], v[130:131] op_sel_hi:[1,0,1]
	v_pk_fma_f32 v[0:1], v[0:1], v[184:185], v[132:133] op_sel_hi:[1,0,1]
	v_pk_fma_f32 v[2:3], v[2:3], v[184:185], v[134:135] op_sel_hi:[1,0,1]
	v_pk_fma_f32 v[182:183], v[4:5], v[4:5], v[182:183]
	v_pk_fma_f32 v[182:183], v[6:7], v[6:7], v[182:183]
	v_pk_fma_f32 v[182:183], v[0:1], v[0:1], v[182:183]
	v_pk_fma_f32 v[182:183], v[2:3], v[2:3], v[182:183]
	v_add_f32_e32 v171, v182, v183
	global_load_dwordx4 v[148:151], v252, s[86:87] offset:0
	global_load_dwordx4 v[152:155], v252, s[86:87] offset:16
	global_load_dwordx4 v[156:159], v252, s[86:87] offset:512
	global_load_dwordx4 v[160:163], v252, s[86:87] offset:528
	v_xor_b32_e32 v128, 16, v186
	v_xor_b32_e32 v129, 32, v186
	v_lshlrev_b32_e32 v128, 2, v128
	v_lshlrev_b32_e32 v129, 2, v129
	ds_bpermute_b32 v188, v128, v164
	ds_bpermute_b32 v189, v128, v165
	ds_bpermute_b32 v190, v128, v166
	ds_bpermute_b32 v191, v128, v167
	ds_bpermute_b32 v192, v128, v168
	ds_bpermute_b32 v193, v128, v169
	ds_bpermute_b32 v194, v128, v170
	ds_bpermute_b32 v195, v128, v171
	s_waitcnt lgkmcnt(7)
	v_add_f32_e32 v164, v164, v188
	s_waitcnt lgkmcnt(6)
	v_add_f32_e32 v165, v165, v189
	s_waitcnt lgkmcnt(5)
	v_add_f32_e32 v166, v166, v190
	s_waitcnt lgkmcnt(4)
	v_add_f32_e32 v167, v167, v191
	s_waitcnt lgkmcnt(3)
	v_add_f32_e32 v168, v168, v192
	s_waitcnt lgkmcnt(2)
	v_add_f32_e32 v169, v169, v193
	s_waitcnt lgkmcnt(1)
	v_add_f32_e32 v170, v170, v194
	s_waitcnt lgkmcnt(0)
	v_add_f32_e32 v171, v171, v195
	ds_bpermute_b32 v188, v129, v164
	ds_bpermute_b32 v189, v129, v165
	ds_bpermute_b32 v190, v129, v166
	ds_bpermute_b32 v191, v129, v167
	ds_bpermute_b32 v192, v129, v168
	ds_bpermute_b32 v193, v129, v169
	ds_bpermute_b32 v194, v129, v170
	ds_bpermute_b32 v195, v129, v171
	v_cmp_eq_u32_e32 vcc, 0, v173
	s_and_saveexec_b64 s[36:37], vcc
	s_waitcnt lgkmcnt(7)
	v_add_f32_e32 v164, v164, v188
	global_atomic_add_f32 v253, v164, s[16:17]
	s_waitcnt lgkmcnt(6)
	v_add_f32_e32 v165, v165, v189
	global_atomic_add_f32 v253, v165, s[16:17] offset:64
	s_waitcnt lgkmcnt(5)
	v_add_f32_e32 v166, v166, v190
	global_atomic_add_f32 v253, v166, s[16:17] offset:128
	s_waitcnt lgkmcnt(4)
	v_add_f32_e32 v167, v167, v191
	global_atomic_add_f32 v253, v167, s[16:17] offset:192
	s_waitcnt lgkmcnt(3)
	v_add_f32_e32 v168, v168, v192
	global_atomic_add_f32 v253, v168, s[16:17] offset:512
	s_waitcnt lgkmcnt(2)
	v_add_f32_e32 v169, v169, v193
	global_atomic_add_f32 v253, v169, s[16:17] offset:576
	s_waitcnt lgkmcnt(1)
	v_add_f32_e32 v170, v170, v194
	global_atomic_add_f32 v253, v170, s[16:17] offset:640
	s_waitcnt lgkmcnt(0)
	v_add_f32_e32 v171, v171, v195
	global_atomic_add_f32 v253, v171, s[16:17] offset:704
	s_or_b64 exec, exec, s[36:37]
	s_lshl_b32 s2, s2, 6
	s_ashr_i32 s3, s2, 31
	s_lshl_b64 s[2:3], s[2:3], 2
	s_waitcnt vmcnt(0)
	s_add_u32 s24, s42, s2
	s_addc_u32 s25, s43, s3
	s_barrier
	v_readlane_b32 s2, v254, 6
	s_nop 3
	s_cmp_lg_u32 s2, 0
	s_cbranch_scc1 .Lp6_poll_done
	v_mov_b32_e32 v181, 1
	s_mov_b64 s[2:3], exec
	s_mov_b64 exec, 1
	global_atomic_add v139, v181, s[24:25]
	s_mov_b64 exec, s[2:3]
	s_mov_b32 s29, 0x100001
.Lp6_spin:
	global_load_dword v181, v139, s[24:25] sc1
	s_waitcnt vmcnt(0)
	v_readfirstlane_b32 s2, v181
	s_cmp_gt_u32 s2, 7
	s_cbranch_scc1 .Lp6_poll_done
	s_add_i32 s29, s29, -1
	s_cmp_eq_u32 s29, 0
	s_cbranch_scc1 .Lp6_poll_done
	s_sleep 1
	s_branch .Lp6_spin
